# attention: packed f32 row sums (17 ops instead of 32), prefetch address as one 64-bit add with SGPR constant
# baseline (speedup 1.0000x reference)
.La1t0_cb:
	v_add_u32_e32 v249, s22, v245
	ds_read_b128 v[128:131], v243 offset:44032
	ds_read_b128 v[132:135], v243 offset:44064
	ds_read_b128 v[136:139], v243 offset:48640
	ds_read_b128 v[140:143], v243 offset:48672
	s_cmp_eq_u64 s[40:41], 0
	s_waitcnt lgkmcnt(11)
	v_mfma_f32_32x32x16_bf16 v[64:79], v[172:175], v[222:225], v[194:209]
	s_cbranch_scc1 .La1t0_nl0
	s_mov_b32 s96, 0xfffe8000
	s_mov_b32 s97, -1
	v_lshl_add_u64 v[186:187], v[190:191], 0, s[96:97]
	global_load_dwordx4 v[96:99], v[186:187], off
.La1t0_nl0:
	s_waitcnt lgkmcnt(10)
	v_mfma_f32_32x32x16_bf16 v[64:79], v[168:171], v[218:221], v[64:79]
	s_cbranch_scc1 .La1t0_nl1
	s_mov_b32 s96, 0xffff0000
	s_mov_b32 s97, -1
	v_lshl_add_u64 v[186:187], v[190:191], 0, s[96:97]
	global_load_dwordx4 v[100:103], v[186:187], off
.La1t0_nl1:
	s_waitcnt lgkmcnt(9)
	v_mfma_f32_32x32x16_bf16 v[64:79], v[164:167], v[214:217], v[64:79]
	s_cbranch_scc1 .La1t0_nl2
	s_mov_b32 s96, 0xffbfff80
	s_mov_b32 s97, -1
	v_lshl_add_u64 v[186:187], v[192:193], 0, s[96:97]
	global_load_dwordx4 v[120:123], v[186:187], off
.La1t0_nl2:
	s_waitcnt lgkmcnt(8)
	v_mfma_f32_32x32x16_bf16 v[64:79], v[160:163], v[210:213], v[64:79]
	s_cbranch_scc1 .La1t0_nl3
	s_mov_b32 s96, 0xffffff80
	s_mov_b32 s97, -1
	v_lshl_add_u64 v[186:187], v[192:193], 0, s[96:97]
	global_load_dwordx4 v[124:127], v[186:187], off

.La1t0_lv_b:
	v_add_u32_e32 v251, 0xd000, v240
	ds_write_b128 v239, v[104:107] offset:17408
	ds_write_b128 v239, v[108:111] offset:26112
	ds_write2_b64 v251, v[112:113], v[114:115] offset1:2
	v_add_u32_e32 v251, 0xf000, v240
	ds_write2_b64 v251, v[116:117], v[118:119] offset0:128 offset1:130
	v_exp_f32_e32 v84, v84
	v_exp_f32_e32 v85, v85
	v_exp_f32_e32 v86, v86
	s_waitcnt lgkmcnt(6)
	v_mfma_f32_32x32x16_bf16 v[16:31], v[132:135], v[164:167], v[16:31]
	ds_read_b128 v[128:131], v243 offset:44096
	ds_read_b128 v[132:135], v243 offset:44128
	v_exp_f32_e32 v87, v87
	v_exp_f32_e32 v88, v88
	v_exp_f32_e32 v89, v89
	s_waitcnt lgkmcnt(7)
	v_mfma_f32_32x32x16_bf16 v[0:15], v[136:139], v[160:163], v[0:15]
	v_exp_f32_e32 v90, v90
	v_exp_f32_e32 v91, v91
	v_exp_f32_e32 v92, v92
	s_waitcnt lgkmcnt(6)
	v_mfma_f32_32x32x16_bf16 v[0:15], v[140:143], v[164:167], v[0:15]
	ds_read_b128 v[136:139], v243 offset:48704
	ds_read_b128 v[140:143], v243 offset:48736
	v_exp_f32_e32 v93, v93
	v_exp_f32_e32 v94, v94
	v_exp_f32_e32 v95, v95
	s_waitcnt lgkmcnt(7)
	v_mfma_f32_32x32x16_bf16 v[48:63], v[144:147], v[160:163], v[48:63]
	v_cvt_pk_bf16_f32 v168, v80, v81
	v_cvt_pk_bf16_f32 v169, v82, v83
	s_waitcnt lgkmcnt(6)
	v_mfma_f32_32x32x16_bf16 v[48:63], v[148:151], v[164:167], v[48:63]
	ds_read_b128 v[144:147], v243 offset:34880
	ds_read_b128 v[148:151], v243 offset:34912
	v_cvt_pk_bf16_f32 v170, v84, v85
	v_cvt_pk_bf16_f32 v171, v86, v87
	s_waitcnt lgkmcnt(7)
	v_mfma_f32_32x32x16_bf16 v[32:47], v[152:155], v[160:163], v[32:47]
	v_cvt_pk_bf16_f32 v172, v88, v89
	v_cvt_pk_bf16_f32 v173, v90, v91
	s_waitcnt lgkmcnt(6)
	v_mfma_f32_32x32x16_bf16 v[32:47], v[156:159], v[164:167], v[32:47]
	ds_read_b128 v[152:155], v243 offset:39488
	ds_read_b128 v[156:159], v243 offset:39520
	v_cvt_pk_bf16_f32 v174, v92, v93
	v_cvt_pk_bf16_f32 v175, v94, v95
	s_nop 1
	s_waitcnt lgkmcnt(7)
	v_mfma_f32_32x32x16_bf16 v[16:31], v[128:131], v[168:171], v[16:31]
	v_pk_add_f32 v[186:187], v[64:65], v[68:69]
	v_pk_add_f32 v[250:251], v[66:67], v[70:71]
	v_pk_add_f32 v[186:187], v[72:73], v[186:187]
	s_waitcnt lgkmcnt(6)
	v_mfma_f32_32x32x16_bf16 v[16:31], v[132:135], v[172:175], v[16:31]
	v_pk_add_f32 v[250:251], v[74:75], v[250:251]
	v_pk_add_f32 v[186:187], v[76:77], v[186:187]
	v_pk_add_f32 v[250:251], v[78:79], v[250:251]
	s_waitcnt lgkmcnt(5)
	v_mfma_f32_32x32x16_bf16 v[0:15], v[136:139], v[168:171], v[0:15]
	v_pk_add_f32 v[186:187], v[80:81], v[186:187]
	v_pk_add_f32 v[250:251], v[82:83], v[250:251]
	v_pk_add_f32 v[186:187], v[84:85], v[186:187]
	s_waitcnt lgkmcnt(4)
	v_mfma_f32_32x32x16_bf16 v[0:15], v[140:143], v[172:175], v[0:15]
	v_pk_add_f32 v[250:251], v[86:87], v[250:251]
	v_pk_add_f32 v[186:187], v[88:89], v[186:187]
	v_pk_add_f32 v[250:251], v[90:91], v[250:251]
	s_waitcnt lgkmcnt(3)
	v_mfma_f32_32x32x16_bf16 v[48:63], v[144:147], v[168:171], v[48:63]
	v_pk_add_f32 v[186:187], v[92:93], v[186:187]
	v_pk_add_f32 v[250:251], v[94:95], v[250:251]
	v_pk_add_f32 v[186:187], v[186:187], v[250:251]
	s_waitcnt lgkmcnt(2)
	v_mfma_f32_32x32x16_bf16 v[48:63], v[148:151], v[172:175], v[48:63]
	v_add_f32_e32 v186, v186, v187
	v_add_f32_e32 v248, v248, v186
	s_waitcnt lgkmcnt(1)
	v_mfma_f32_32x32x16_bf16 v[32:47], v[152:155], v[168:171], v[32:47]
	s_waitcnt lgkmcnt(0)
	v_mfma_f32_32x32x16_bf16 v[32:47], v[156:159], v[172:175], v[32:47]
	s_setprio 0
	s_branch .La1t0_pw
.La1t0_near:
	v_add_u32_e32 v249, s22, v245
	s_mul_i32 s101, s60, 0x704
	s_add_i32 s101, s101, 0x1af80
	v_lshl_add_u32 v251, v249, 2, s101
	ds_read_b32 v64, v251 offset:0
	ds_read_b32 v65, v251 offset:4
	ds_read_b32 v66, v251 offset:8
	ds_read_b32 v67, v251 offset:12
	ds_read_b32 v68, v251 offset:32
	ds_read_b32 v69, v251 offset:36
	ds_read_b32 v70, v251 offset:40
	ds_read_b32 v71, v251 offset:44
	ds_read_b32 v72, v251 offset:64
	ds_read_b32 v73, v251 offset:68
	ds_read_b32 v74, v251 offset:72
	ds_read_b32 v75, v251 offset:76
	ds_read_b32 v76, v251 offset:96
	ds_read_b32 v77, v251 offset:100
	ds_read_b32 v78, v251 offset:104
	ds_read_b32 v79, v251 offset:108
	ds_read_b32 v80, v251 offset:128
	ds_read_b32 v81, v251 offset:132
	ds_read_b32 v82, v251 offset:136
	ds_read_b32 v83, v251 offset:140
	ds_read_b32 v84, v251 offset:160
	ds_read_b32 v85, v251 offset:164
	ds_read_b32 v86, v251 offset:168
	ds_read_b32 v87, v251 offset:172
	ds_read_b32 v88, v251 offset:192
	ds_read_b32 v89, v251 offset:196
	ds_read_b32 v90, v251 offset:200
	ds_read_b32 v91, v251 offset:204
	ds_read_b32 v92, v251 offset:224
	ds_read_b32 v93, v251 offset:228
	ds_read_b32 v94, v251 offset:232
	ds_read_b32 v95, v251 offset:236
	s_waitcnt lgkmcnt(0)
	ds_read_b128 v[128:131], v243 offset:44032
	ds_read_b128 v[132:135], v243 offset:44064
	ds_read_b128 v[136:139], v243 offset:48640
	ds_read_b128 v[140:143], v243 offset:48672
	s_cmp_eq_u64 s[40:41], 0
	v_mfma_f32_32x32x16_bf16 v[64:79], v[172:175], v[222:225], v[64:79]
	s_cbranch_scc1 .La1t0n_nl0
	s_mov_b32 s96, 0xfffe8000
	s_mov_b32 s97, -1
	v_lshl_add_u64 v[186:187], v[190:191], 0, s[96:97]
	global_load_dwordx4 v[96:99], v[186:187], off
.La1t0n_nl0:
	v_mfma_f32_32x32x16_bf16 v[64:79], v[168:171], v[218:221], v[64:79]
	s_cbranch_scc1 .La1t0n_nl1
	s_mov_b32 s96, 0xffff0000
	s_mov_b32 s97, -1
	v_lshl_add_u64 v[186:187], v[190:191], 0, s[96:97]
	global_load_dwordx4 v[100:103], v[186:187], off
.La1t0n_nl1:
	v_mfma_f32_32x32x16_bf16 v[64:79], v[164:167], v[214:217], v[64:79]
	s_cbranch_scc1 .La1t0n_nl2
	s_mov_b32 s96, 0xffbfff80
	s_mov_b32 s97, -1
	v_lshl_add_u64 v[186:187], v[192:193], 0, s[96:97]
	global_load_dwordx4 v[120:123], v[186:187], off
.La1t0n_nl2:
	v_mfma_f32_32x32x16_bf16 v[64:79], v[160:163], v[210:213], v[64:79]
	s_cbranch_scc1 .La1t0n_nl3
	s_mov_b32 s96, 0xffffff80
	s_mov_b32 s97, -1
	v_lshl_add_u64 v[186:187], v[192:193], 0, s[96:97]
	global_load_dwordx4 v[124:127], v[186:187], off

.La1t1_cb:
	ds_read_b128 v[128:131], v243 offset:62464
	ds_read_b128 v[132:135], v243 offset:62496
	ds_read_b128 v[136:139], v244 offset:13824
	ds_read_b128 v[140:143], v244 offset:13856
	s_cmp_eq_u64 s[40:41], 0
	s_waitcnt lgkmcnt(11)
	v_mfma_f32_32x32x16_bf16 v[64:79], v[172:175], v[222:225], v[194:209]
	s_cbranch_scc1 .La1t1_nl0
	s_mov_b32 s96, 0xffff8000
	s_mov_b32 s97, -1
	v_lshl_add_u64 v[186:187], v[190:191], 0, s[96:97]
	global_load_dwordx4 v[104:107], v[186:187], off

.La1t1_nl1:
	s_waitcnt lgkmcnt(9)
	v_mfma_f32_32x32x16_bf16 v[64:79], v[164:167], v[214:217], v[64:79]
	s_cbranch_scc1 .La1t1_nl2
	s_mov_b32 s96, 0xffc00000
	s_mov_b32 s97, -1
	v_lshl_add_u64 v[186:187], v[192:193], 0, s[96:97]
	global_load_dwordx4 v[112:115], v[186:187], off

.La1t1_lv_s:
	v_exp_f32_e32 v84, v84
	v_exp_f32_e32 v85, v85
	v_exp_f32_e32 v86, v86
	s_waitcnt lgkmcnt(6)
	v_mfma_f32_32x32x16_bf16 v[16:31], v[132:135], v[164:167], v[16:31]
	ds_read_b128 v[128:131], v243 offset:62528
	ds_read_b128 v[132:135], v243 offset:62560
	v_exp_f32_e32 v87, v87
	v_exp_f32_e32 v88, v88
	v_exp_f32_e32 v89, v89
	s_waitcnt lgkmcnt(7)
	v_mfma_f32_32x32x16_bf16 v[0:15], v[136:139], v[160:163], v[0:15]
	v_exp_f32_e32 v90, v90
	v_exp_f32_e32 v91, v91
	v_exp_f32_e32 v92, v92
	s_waitcnt lgkmcnt(6)
	v_mfma_f32_32x32x16_bf16 v[0:15], v[140:143], v[164:167], v[0:15]
	ds_read_b128 v[136:139], v244 offset:13888
	ds_read_b128 v[140:143], v244 offset:13920
	v_exp_f32_e32 v93, v93
	v_exp_f32_e32 v94, v94
	v_exp_f32_e32 v95, v95
	s_waitcnt lgkmcnt(7)
	v_mfma_f32_32x32x16_bf16 v[48:63], v[144:147], v[160:163], v[48:63]
	v_cvt_pk_bf16_f32 v168, v80, v81
	v_cvt_pk_bf16_f32 v169, v82, v83
	s_waitcnt lgkmcnt(6)
	v_mfma_f32_32x32x16_bf16 v[48:63], v[148:151], v[164:167], v[48:63]
	ds_read_b128 v[144:147], v243 offset:53312
	ds_read_b128 v[148:151], v243 offset:53344
	v_cvt_pk_bf16_f32 v170, v84, v85
	v_cvt_pk_bf16_f32 v171, v86, v87
	s_waitcnt lgkmcnt(7)
	v_mfma_f32_32x32x16_bf16 v[32:47], v[152:155], v[160:163], v[32:47]
	v_cvt_pk_bf16_f32 v172, v88, v89
	v_cvt_pk_bf16_f32 v173, v90, v91
	s_waitcnt lgkmcnt(6)
	v_mfma_f32_32x32x16_bf16 v[32:47], v[156:159], v[164:167], v[32:47]
	ds_read_b128 v[152:155], v243 offset:57920
	ds_read_b128 v[156:159], v243 offset:57952
	v_cvt_pk_bf16_f32 v174, v92, v93
	v_cvt_pk_bf16_f32 v175, v94, v95
	s_nop 1
	s_waitcnt lgkmcnt(7)
	v_mfma_f32_32x32x16_bf16 v[16:31], v[128:131], v[168:171], v[16:31]
	v_pk_add_f32 v[186:187], v[64:65], v[68:69]
	v_pk_add_f32 v[250:251], v[66:67], v[70:71]
	v_pk_add_f32 v[186:187], v[72:73], v[186:187]
	s_waitcnt lgkmcnt(6)
	v_mfma_f32_32x32x16_bf16 v[16:31], v[132:135], v[172:175], v[16:31]
	v_pk_add_f32 v[250:251], v[74:75], v[250:251]
	v_pk_add_f32 v[186:187], v[76:77], v[186:187]
	v_pk_add_f32 v[250:251], v[78:79], v[250:251]
	s_waitcnt lgkmcnt(5)
	v_mfma_f32_32x32x16_bf16 v[0:15], v[136:139], v[168:171], v[0:15]
	v_pk_add_f32 v[186:187], v[80:81], v[186:187]
	v_pk_add_f32 v[250:251], v[82:83], v[250:251]
	v_pk_add_f32 v[186:187], v[84:85], v[186:187]
	s_waitcnt lgkmcnt(4)
	v_mfma_f32_32x32x16_bf16 v[0:15], v[140:143], v[172:175], v[0:15]
	v_pk_add_f32 v[250:251], v[86:87], v[250:251]
	v_pk_add_f32 v[186:187], v[88:89], v[186:187]
	v_pk_add_f32 v[250:251], v[90:91], v[250:251]
	s_waitcnt lgkmcnt(3)
	v_mfma_f32_32x32x16_bf16 v[48:63], v[144:147], v[168:171], v[48:63]
	v_pk_add_f32 v[186:187], v[92:93], v[186:187]
	v_pk_add_f32 v[250:251], v[94:95], v[250:251]
	v_pk_add_f32 v[186:187], v[186:187], v[250:251]
	s_waitcnt lgkmcnt(2)
	v_mfma_f32_32x32x16_bf16 v[48:63], v[148:151], v[172:175], v[48:63]
	v_add_f32_e32 v186, v186, v187
	v_add_f32_e32 v248, v248, v186
	s_waitcnt lgkmcnt(1)
	v_mfma_f32_32x32x16_bf16 v[32:47], v[152:155], v[168:171], v[32:47]
	s_waitcnt lgkmcnt(0)
	v_mfma_f32_32x32x16_bf16 v[32:47], v[156:159], v[172:175], v[32:47]
	s_setprio 0
	s_branch .LBB0_583
.La1t1_near:
	s_mul_i32 s101, s60, 0x704
	s_add_i32 s101, s101, 0x1b080
	v_lshl_add_u32 v251, v249, 2, s101
	ds_read_b32 v64, v251 offset:0
	ds_read_b32 v65, v251 offset:4
	ds_read_b32 v66, v251 offset:8
	ds_read_b32 v67, v251 offset:12
	ds_read_b32 v68, v251 offset:32
	ds_read_b32 v69, v251 offset:36
	ds_read_b32 v70, v251 offset:40
	ds_read_b32 v71, v251 offset:44
	ds_read_b32 v72, v251 offset:64
	ds_read_b32 v73, v251 offset:68
	ds_read_b32 v74, v251 offset:72
	ds_read_b32 v75, v251 offset:76
	ds_read_b32 v76, v251 offset:96
	ds_read_b32 v77, v251 offset:100
	ds_read_b32 v78, v251 offset:104
	ds_read_b32 v79, v251 offset:108
	ds_read_b32 v80, v251 offset:128
	ds_read_b32 v81, v251 offset:132
	ds_read_b32 v82, v251 offset:136
	ds_read_b32 v83, v251 offset:140
	ds_read_b32 v84, v251 offset:160
	ds_read_b32 v85, v251 offset:164
	ds_read_b32 v86, v251 offset:168
	ds_read_b32 v87, v251 offset:172
	ds_read_b32 v88, v251 offset:192
	ds_read_b32 v89, v251 offset:196
	ds_read_b32 v90, v251 offset:200
	ds_read_b32 v91, v251 offset:204
	ds_read_b32 v92, v251 offset:224
	ds_read_b32 v93, v251 offset:228
	ds_read_b32 v94, v251 offset:232
	ds_read_b32 v95, v251 offset:236
	s_waitcnt lgkmcnt(0)
	ds_read_b128 v[128:131], v243 offset:62464
	ds_read_b128 v[132:135], v243 offset:62496
	ds_read_b128 v[136:139], v244 offset:13824
	ds_read_b128 v[140:143], v244 offset:13856
	s_cmp_eq_u64 s[40:41], 0
	v_mfma_f32_32x32x16_bf16 v[64:79], v[172:175], v[222:225], v[64:79]
	s_cbranch_scc1 .La1t1n_nl0
	s_mov_b32 s96, 0xffff8000
	s_mov_b32 s97, -1
	v_lshl_add_u64 v[186:187], v[190:191], 0, s[96:97]
	global_load_dwordx4 v[104:107], v[186:187], off

.La1t1n_nl1:
	v_mfma_f32_32x32x16_bf16 v[64:79], v[164:167], v[214:217], v[64:79]
	s_cbranch_scc1 .La1t1n_nl2
	s_mov_b32 s96, 0xffc00000
	s_mov_b32 s97, -1
	v_lshl_add_u64 v[186:187], v[192:193], 0, s[96:97]
	global_load_dwordx4 v[112:115], v[186:187], off

.La2t0_cb:
	v_add_u32_e32 v249, s42, v245
	ds_read_b128 v[128:131], v243 offset:44032
	ds_read_b128 v[132:135], v243 offset:44064
	ds_read_b128 v[136:139], v243 offset:48640
	ds_read_b128 v[140:143], v243 offset:48672
	s_cmp_eq_u64 s[0:1], 0
	s_waitcnt lgkmcnt(11)
	v_mfma_f32_32x32x16_bf16 v[64:79], v[172:175], v[222:225], v[194:209]
	s_cbranch_scc1 .La2t0_nl0
	s_mov_b32 s96, 0xfffe8000
	s_mov_b32 s97, -1
	v_lshl_add_u64 v[186:187], v[192:193], 0, s[96:97]
	global_load_dwordx4 v[96:99], v[186:187], off
.La2t0_nl0:
	s_waitcnt lgkmcnt(10)
	v_mfma_f32_32x32x16_bf16 v[64:79], v[168:171], v[218:221], v[64:79]
	s_cbranch_scc1 .La2t0_nl1
	s_mov_b32 s96, 0xffff0000
	s_mov_b32 s97, -1
	v_lshl_add_u64 v[186:187], v[192:193], 0, s[96:97]
	global_load_dwordx4 v[100:103], v[186:187], off
.La2t0_nl1:
	s_waitcnt lgkmcnt(9)
	v_mfma_f32_32x32x16_bf16 v[64:79], v[164:167], v[214:217], v[64:79]
	s_cbranch_scc1 .La2t0_nl2
	s_mov_b32 s96, 0xffbfff80
	s_mov_b32 s97, -1
	v_lshl_add_u64 v[186:187], v[190:191], 0, s[96:97]
	global_load_dwordx4 v[120:123], v[186:187], off
.La2t0_nl2:
	s_waitcnt lgkmcnt(8)
	v_mfma_f32_32x32x16_bf16 v[64:79], v[160:163], v[210:213], v[64:79]
	s_cbranch_scc1 .La2t0_nl3
	s_mov_b32 s96, 0xffffff80
	s_mov_b32 s97, -1
	v_lshl_add_u64 v[186:187], v[190:191], 0, s[96:97]
	global_load_dwordx4 v[124:127], v[186:187], off

.La2t0_near:
	v_add_u32_e32 v249, s42, v245
	s_mul_i32 s101, s60, 0x704
	s_add_i32 s101, s101, 0x1af80
	v_lshl_add_u32 v251, v249, 2, s101
	ds_read_b32 v64, v251 offset:0
	ds_read_b32 v65, v251 offset:4
	ds_read_b32 v66, v251 offset:8
	ds_read_b32 v67, v251 offset:12
	ds_read_b32 v68, v251 offset:32
	ds_read_b32 v69, v251 offset:36
	ds_read_b32 v70, v251 offset:40
	ds_read_b32 v71, v251 offset:44
	ds_read_b32 v72, v251 offset:64
	ds_read_b32 v73, v251 offset:68
	ds_read_b32 v74, v251 offset:72
	ds_read_b32 v75, v251 offset:76
	ds_read_b32 v76, v251 offset:96
	ds_read_b32 v77, v251 offset:100
	ds_read_b32 v78, v251 offset:104
	ds_read_b32 v79, v251 offset:108
	ds_read_b32 v80, v251 offset:128
	ds_read_b32 v81, v251 offset:132
	ds_read_b32 v82, v251 offset:136
	ds_read_b32 v83, v251 offset:140
	ds_read_b32 v84, v251 offset:160
	ds_read_b32 v85, v251 offset:164
	ds_read_b32 v86, v251 offset:168
	ds_read_b32 v87, v251 offset:172
	ds_read_b32 v88, v251 offset:192
	ds_read_b32 v89, v251 offset:196
	ds_read_b32 v90, v251 offset:200
	ds_read_b32 v91, v251 offset:204
	ds_read_b32 v92, v251 offset:224
	ds_read_b32 v93, v251 offset:228
	ds_read_b32 v94, v251 offset:232
	ds_read_b32 v95, v251 offset:236
	s_waitcnt lgkmcnt(0)
	ds_read_b128 v[128:131], v243 offset:44032
	ds_read_b128 v[132:135], v243 offset:44064
	ds_read_b128 v[136:139], v243 offset:48640
	ds_read_b128 v[140:143], v243 offset:48672
	s_cmp_eq_u64 s[0:1], 0
	v_mfma_f32_32x32x16_bf16 v[64:79], v[172:175], v[222:225], v[64:79]
	s_cbranch_scc1 .La2t0n_nl0
	s_mov_b32 s96, 0xfffe8000
	s_mov_b32 s97, -1
	v_lshl_add_u64 v[186:187], v[192:193], 0, s[96:97]
	global_load_dwordx4 v[96:99], v[186:187], off
.La2t0n_nl0:
	v_mfma_f32_32x32x16_bf16 v[64:79], v[168:171], v[218:221], v[64:79]
	s_cbranch_scc1 .La2t0n_nl1
	s_mov_b32 s96, 0xffff0000
	s_mov_b32 s97, -1
	v_lshl_add_u64 v[186:187], v[192:193], 0, s[96:97]
	global_load_dwordx4 v[100:103], v[186:187], off
.La2t0n_nl1:
	v_mfma_f32_32x32x16_bf16 v[64:79], v[164:167], v[214:217], v[64:79]
	s_cbranch_scc1 .La2t0n_nl2
	s_mov_b32 s96, 0xffbfff80
	s_mov_b32 s97, -1
	v_lshl_add_u64 v[186:187], v[190:191], 0, s[96:97]
	global_load_dwordx4 v[120:123], v[186:187], off
.La2t0n_nl2:
	v_mfma_f32_32x32x16_bf16 v[64:79], v[160:163], v[210:213], v[64:79]
	s_cbranch_scc1 .La2t0n_nl3
	s_mov_b32 s96, 0xffffff80
	s_mov_b32 s97, -1
	v_lshl_add_u64 v[186:187], v[190:191], 0, s[96:97]
	global_load_dwordx4 v[124:127], v[186:187], off

.La2t1_cb:
	ds_read_b128 v[128:131], v243 offset:62464
	ds_read_b128 v[132:135], v243 offset:62496
	ds_read_b128 v[136:139], v244 offset:13824
	ds_read_b128 v[140:143], v244 offset:13856
	s_cmp_eq_u64 s[0:1], 0
	s_waitcnt lgkmcnt(11)
	v_mfma_f32_32x32x16_bf16 v[64:79], v[172:175], v[222:225], v[194:209]
	s_cbranch_scc1 .La2t1_nl0
	s_mov_b32 s96, 0xffff8000
	s_mov_b32 s97, -1
	v_lshl_add_u64 v[186:187], v[192:193], 0, s[96:97]
	global_load_dwordx4 v[104:107], v[186:187], off

.La2t1_nl1:
	s_waitcnt lgkmcnt(9)
	v_mfma_f32_32x32x16_bf16 v[64:79], v[164:167], v[214:217], v[64:79]
	s_cbranch_scc1 .La2t1_nl2
	s_mov_b32 s96, 0xffc00000
	s_mov_b32 s97, -1
	v_lshl_add_u64 v[186:187], v[190:191], 0, s[96:97]
	global_load_dwordx4 v[112:115], v[186:187], off

.La2t1_near:
	s_mul_i32 s101, s60, 0x704
	s_add_i32 s101, s101, 0x1b080
	v_lshl_add_u32 v251, v249, 2, s101
	ds_read_b32 v64, v251 offset:0
	ds_read_b32 v65, v251 offset:4
	ds_read_b32 v66, v251 offset:8
	ds_read_b32 v67, v251 offset:12
	ds_read_b32 v68, v251 offset:32
	ds_read_b32 v69, v251 offset:36
	ds_read_b32 v70, v251 offset:40
	ds_read_b32 v71, v251 offset:44
	ds_read_b32 v72, v251 offset:64
	ds_read_b32 v73, v251 offset:68
	ds_read_b32 v74, v251 offset:72
	ds_read_b32 v75, v251 offset:76
	ds_read_b32 v76, v251 offset:96
	ds_read_b32 v77, v251 offset:100
	ds_read_b32 v78, v251 offset:104
	ds_read_b32 v79, v251 offset:108
	ds_read_b32 v80, v251 offset:128
	ds_read_b32 v81, v251 offset:132
	ds_read_b32 v82, v251 offset:136
	ds_read_b32 v83, v251 offset:140
	ds_read_b32 v84, v251 offset:160
	ds_read_b32 v85, v251 offset:164
	ds_read_b32 v86, v251 offset:168
	ds_read_b32 v87, v251 offset:172
	ds_read_b32 v88, v251 offset:192
	ds_read_b32 v89, v251 offset:196
	ds_read_b32 v90, v251 offset:200
	ds_read_b32 v91, v251 offset:204
	ds_read_b32 v92, v251 offset:224
	ds_read_b32 v93, v251 offset:228
	ds_read_b32 v94, v251 offset:232
	ds_read_b32 v95, v251 offset:236
	s_waitcnt lgkmcnt(0)
	ds_read_b128 v[128:131], v243 offset:62464
	ds_read_b128 v[132:135], v243 offset:62496
	ds_read_b128 v[136:139], v244 offset:13824
	ds_read_b128 v[140:143], v244 offset:13856
	s_cmp_eq_u64 s[0:1], 0
	v_mfma_f32_32x32x16_bf16 v[64:79], v[172:175], v[222:225], v[64:79]
	s_cbranch_scc1 .La2t1n_nl0
	s_mov_b32 s96, 0xffff8000
	s_mov_b32 s97, -1
	v_lshl_add_u64 v[186:187], v[192:193], 0, s[96:97]
	global_load_dwordx4 v[104:107], v[186:187], off

.La2t1n_nl1:
	v_mfma_f32_32x32x16_bf16 v[64:79], v[164:167], v[214:217], v[64:79]
	s_cbranch_scc1 .La2t1n_nl2
	s_mov_b32 s96, 0xffc00000
	s_mov_b32 s97, -1
	v_lshl_add_u64 v[186:187], v[190:191], 0, s[96:97]
	global_load_dwordx4 v[112:115], v[186:187], off
